# hand-written software-pipelined weight-conversion loop in prep phase (4 tiles in flight, lane-cached descriptors)
# speedup vs baseline: 1.0122x; 1.0122x over previous
.LBB0_7:
	s_or_b64 exec, exec, s[4:5]
	s_load_dword s2, s[0:1], 0x40c
	v_mov_b32_e32 v2, v189
	s_waitcnt lgkmcnt(0)
	s_add_i32 s14, s2, 0x140
	s_cmp_ge_i32 s73, s14
	s_cbranch_scc1 .LBB0_57
	s_add_i32 s15, s2, 0xc0
	v_and_b32_e32 v3, 15, v2
	v_lshlrev_b32_e32 v4, 3, v3
	v_mov_b32_e32 v5, 0
	s_getpc_b64 s[4:5]
	s_add_u32 s4, s4, c_invf@rel32@lo+4
	s_addc_u32 s5, s5, c_invf@rel32@hi+12
	v_lshl_add_u64 v[6:7], s[4:5], 0, v[4:5]
	v_and_b32_e32 v4, 16, v2
	v_bfe_i32 v8, v2, 4, 1
	s_movk_i32 s18, 0xb00
	v_cmp_eq_u32_e64 s[4:5], 0, v4
	v_and_b32_e32 v52, 63, v2
	v_and_or_b32 v53, v8, s18, v3
	v_lshlrev_b32_e32 v4, 6, v2
	s_movk_i32 s18, 0x400
	v_ashrrev_i32_e32 v55, 3, v2
	v_lshlrev_b32_e32 v12, 3, v2
	v_and_or_b32 v3, v4, s18, v3
	v_and_b32_e32 v56, -8, v55
	v_lshlrev_b32_e32 v4, 2, v52
	s_movk_i32 s20, 0x104
	v_or_b32_e32 v68, 7, v55
	v_mad_u64_u32 v[8:9], s[18:19], v56, s20, v[4:5]
	v_mad_u64_u32 v[10:11], s[18:19], v68, s20, v[4:5]
	v_and_b32_e32 v4, 56, v12
	v_ashrrev_i32_e32 v20, 6, v2
	s_add_u32 s24, s16, 0x80000
	v_add_u32_e32 v54, 0x400, v3
	v_mul_u32_u24_e32 v3, 0x41, v4
	v_and_b32_e32 v69, 0x7f, v2
	s_addc_u32 s25, s17, 0
	v_lshlrev_b32_e32 v18, 7, v20
	v_and_b32_e32 v21, 0x1f8, v12
	v_lshlrev_b32_e32 v3, 2, v3
	s_movk_i32 s18, 0xa00
	v_lshlrev_b32_e32 v12, 2, v69
	v_mov_b32_e32 v13, v5
	s_movk_i32 s21, 0x6000
	s_movk_i32 s6, 0x1400
	s_movk_i32 s8, 0x280
	v_lshl_add_u32 v11, v55, 2, v3
	v_mul_lo_u32 v22, v20, s18
	v_lshl_add_u64 v[14:15], s[16:17], 0, v[12:13]
	v_ashrrev_i32_e32 v3, 31, v2
	v_mad_i64_i32 v[18:19], s[16:17], v18, s21, 0
	s_add_u32 s26, s0, 0x400
	s_mov_b32 s28, 0x6dc9c883
	s_mov_b32 s30, 0x54442d18
	s_mov_b32 s34, 0x13a86d09
	s_mov_b32 s36, 0xeff8d898
	v_add_u32_e32 v1, 0xfffe8000, v2
	v_cmp_gt_i32_e64 s[6:7], s6, v2
	v_cmp_gt_i32_e64 s[8:9], s8, v2
	v_or_b32_e32 v9, 1, v56
	v_add_u32_e32 v57, 0x104, v8
	v_or_b32_e32 v58, 2, v56
	v_add_u32_e32 v59, 0x208, v8
	v_or_b32_e32 v60, 3, v56
	v_add_u32_e32 v61, 0x30c, v8
	v_or_b32_e32 v62, 4, v56
	v_add_u32_e32 v63, 0x410, v8
	v_or_b32_e32 v64, 5, v56
	v_add_u32_e32 v65, 0x514, v8
	v_or_b32_e32 v66, 6, v56
	v_add_u32_e32 v67, 0x618, v8
	s_movk_i32 s20, 0x7f
	v_lshlrev_b64 v[16:17], 2, v[2:3]
	v_lshlrev_b32_e32 v3, 2, v2
	v_lshl_or_b32 v18, v52, 3, v18
	v_lshlrev_b32_e32 v13, 9, v20
	s_addc_u32 s27, s1, 0
	s_mov_b32 s29, 0x3fe45f30
	s_mov_b32 s31, 0xbff921fb
	s_mov_b32 s35, 0x3de61246
	s_mov_b32 s37, 0x3e21eed8
	s_movk_i32 s33, 0xfff
	s_movk_i32 s46, 0x3ff
	s_mov_b64 s[38:39], 0x800
	s_movk_i32 s47, 0x11ff
	s_mov_b32 s48, 0xc000
	s_mov_b32 s49, 0x12000
	v_add_u32_e32 v70, v21, v22
	v_lshlrev_b32_e32 v20, 1, v4
	v_mov_b32_e32 v22, 0x67f544e4
	v_mov_b32_e32 v23, 0xbe5ae645
	v_mov_b32_e32 v24, 0xa556c734
	v_mov_b32_e32 v25, 0x3ec71de3
	v_mov_b32_e32 v26, 0x1a01a01a
	v_mov_b32_e32 v27, 0xbf2a01a0
	v_mov_b32_e32 v28, 0x11111111
	v_mov_b32_e32 v29, 0x3f811111
	v_mov_b32_e32 v30, 0x55555555
	v_mov_b32_e32 v31, 0xbfc55555
	v_mov_b32_e32 v32, 0xb7789f5c
	v_mov_b32_e32 v33, 0xbe927e4f
	v_mov_b32_e32 v35, 0x3efa01a0
	v_mov_b32_e32 v36, 0x16c16c17
	v_mov_b32_e32 v37, 0xbf56c16c
	v_mov_b32_e32 v39, 0x3fa55555
	v_add_u32_e32 v71, 0x400, v11
	v_and_b32_e32 v114, 63, v189
	v_lshrrev_b32_e32 v115, 3, v189
	v_and_b32_e32 v115, 56, v115
	v_mul_u32_u24_e32 v116, 0x41, v115
	v_add_lshl_u32 v116, v116, v114, 2
	v_lshrrev_b32_e32 v117, 3, v189
	v_and_b32_e32 v118, 7, v189
	v_lshlrev_b32_e32 v118, 3, v118
	v_mul_u32_u24_e32 v119, 0x41, v118
	v_add_lshl_u32 v119, v119, v117, 2
	v_add_u32_e32 v131, 0x410, v119
	v_add_u32_e32 v143, 0x4100, v119
	v_add_u32_e32 v155, 0x4510, v119
	v_mul_u32_u24_e32 v168, 40, v114
	v_add_u32_e32 v168, 0xe8, v168
	v_bfrev_b32_e32 v106, -2
	v_cmp_gt_u32_e32 vcc, 20, v114
	s_and_saveexec_b64 s[88:89], vcc
	global_load_dword v106, v168, s[0:1] offset:32
	global_load_dword v107, v168, s[0:1] offset:0
	global_load_dword v108, v168, s[0:1] offset:4
	global_load_dword v109, v168, s[0:1] offset:8
	global_load_dword v110, v168, s[0:1] offset:12
	global_load_dword v111, v168, s[0:1] offset:16
	global_load_dword v112, v168, s[0:1] offset:20
	global_load_dword v113, v168, s[0:1] offset:28
	s_mov_b64 exec, s[88:89]
	s_waitcnt vmcnt(0)
	s_mov_b32 s68, s73
	s_mov_b32 s69, s73
	s_mul_i32 s72, s3, 3
	s_cmp_ge_i32 s68, s2
	s_cbranch_scc1 .Lcv_pro_done
	v_cmp_le_i32_e64 s[88:89], v106, s68
	s_nop 1
	s_bcnt1_i32_b64 s74, s[88:89]
	s_sub_u32 s74, s74, 1
	s_nop 3
	v_readlane_b32 s67, v106, s74
	v_readlane_b32 s60, v107, s74
	v_readlane_b32 s61, v108, s74
	v_readlane_b32 s62, v109, s74
	v_readlane_b32 s63, v110, s74
	v_readlane_b32 s64, v111, s74
	v_readlane_b32 s65, v112, s74
	v_readlane_b32 s66, v113, s74
	s_nop 3
	s_sub_u32 s75, s68, s67
	s_lshr_b32 s90, s64, 6
	s_mov_b32 s91, 0x10000000
	s_cmp_eq_u32 s90, 6
	s_cselect_b32 s91, 0x2aaaaaab, s91
	s_cmp_eq_u32 s90, 4
	s_cselect_b32 s91, 0x40000000, s91
	s_cmp_eq_u32 s90, 44
	s_cselect_b32 s91, 0x5d1745e, s91
	s_cmp_eq_u32 s90, 32
	s_cselect_b32 s91, 0x8000000, s91
	s_mul_hi_u32 s92, s75, s91
	s_mul_i32 s93, s92, s90
	s_sub_u32 s93, s75, s93
	s_lshl_b32 s92, s92, 6
	s_lshl_b32 s93, s93, 6
	s_cmp_lt_u32 s92, s65
	s_cselect_b32 s94, -1, 0
	s_cselect_b32 s95, s92, 0
	v_add_u32_e32 v168, s92, v117
	v_mul_lo_u32 v168, v168, s64
	v_add3_u32 v168, v168, v118, s93
	v_lshlrev_b32_e32 v168, 1, v168
	v_mov_b32_e32 v169, 0
	v_lshl_add_u64 v[128:129], v[168:169], 0, s[62:63]
	v_mov_b32_e32 v130, s94
	v_add_u32_e32 v168, s95, v114
	s_cmp_eq_u32 s66, 0
	s_cbranch_scc1 .Lcv_sc_done_p0
	s_cmp_eq_u32 s66, 2
	s_cbranch_scc1 .Lcv_sc_m2_p0
	s_cmpk_lt_u32 s95, 0x400
	s_cbranch_scc1 .Lcv_sc_done_p0
	v_add_u32_e32 v168, 0xfffffc00, v168
	v_lshrrev_b32_e32 v169, 5, v168
	v_lshlrev_b32_e32 v169, 4, v169
	v_and_b32_e32 v170, 15, v168
	v_bfe_u32 v171, v168, 4, 1
	v_lshlrev_b32_e32 v171, 10, v171
	v_add3_u32 v168, v169, v170, v171
	v_add_u32_e32 v168, 0x400, v168
	s_branch .Lcv_sc_done_p0
.Lcv_sc_m2_p0:
	v_lshrrev_b32_e32 v169, 5, v168
	v_lshlrev_b32_e32 v169, 4, v169
	v_and_b32_e32 v170, 15, v168
	v_bfe_u32 v171, v168, 4, 1
	v_mul_u32_u24_e32 v171, 0xb00, v171
	v_add3_u32 v168, v169, v170, v171
.Lcv_sc_done_p0:
	v_add_u32_e32 v169, s93, v115
	v_mul_lo_u32 v169, v169, s65
	v_add_lshl_u32 v120, v169, v168, 2
	s_lshl_b32 s96, s65, 2
	v_add_u32_e32 v121, s96, v120
	v_add_u32_e32 v122, s96, v121
	v_add_u32_e32 v123, s96, v122
	v_add_u32_e32 v124, s96, v123
	v_add_u32_e32 v125, s96, v124
	v_add_u32_e32 v126, s96, v125
	v_add_u32_e32 v127, s96, v126
	global_load_dword v120, v120, s[60:61]
	global_load_dword v121, v121, s[60:61]
	global_load_dword v122, v122, s[60:61]
	global_load_dword v123, v123, s[60:61]
	global_load_dword v124, v124, s[60:61]
	global_load_dword v125, v125, s[60:61]
	global_load_dword v126, v126, s[60:61]
	global_load_dword v127, v127, s[60:61]
	s_add_i32 s68, s68, s3
	s_cmp_ge_i32 s68, s2
	s_cbranch_scc1 .Lcv_pro_done
	v_cmp_le_i32_e64 s[88:89], v106, s68
	s_nop 1
	s_bcnt1_i32_b64 s74, s[88:89]
	s_sub_u32 s74, s74, 1
	s_nop 3
	v_readlane_b32 s67, v106, s74
	v_readlane_b32 s60, v107, s74
	v_readlane_b32 s61, v108, s74
	v_readlane_b32 s62, v109, s74
	v_readlane_b32 s63, v110, s74
	v_readlane_b32 s64, v111, s74
	v_readlane_b32 s65, v112, s74
	v_readlane_b32 s66, v113, s74
	s_nop 3
	s_sub_u32 s75, s68, s67
	s_lshr_b32 s90, s64, 6
	s_mov_b32 s91, 0x10000000
	s_cmp_eq_u32 s90, 6
	s_cselect_b32 s91, 0x2aaaaaab, s91
	s_cmp_eq_u32 s90, 4
	s_cselect_b32 s91, 0x40000000, s91
	s_cmp_eq_u32 s90, 44
	s_cselect_b32 s91, 0x5d1745e, s91
	s_cmp_eq_u32 s90, 32
	s_cselect_b32 s91, 0x8000000, s91
	s_mul_hi_u32 s92, s75, s91
	s_mul_i32 s93, s92, s90
	s_sub_u32 s93, s75, s93
	s_lshl_b32 s92, s92, 6
	s_lshl_b32 s93, s93, 6
	s_cmp_lt_u32 s92, s65
	s_cselect_b32 s94, -1, 0
	s_cselect_b32 s95, s92, 0
	v_add_u32_e32 v168, s92, v117
	v_mul_lo_u32 v168, v168, s64
	v_add3_u32 v168, v168, v118, s93
	v_lshlrev_b32_e32 v168, 1, v168
	v_mov_b32_e32 v169, 0
	v_lshl_add_u64 v[140:141], v[168:169], 0, s[62:63]
	v_mov_b32_e32 v142, s94
	v_add_u32_e32 v168, s95, v114
	s_cmp_eq_u32 s66, 0
	s_cbranch_scc1 .Lcv_sc_done_p1
	s_cmp_eq_u32 s66, 2
	s_cbranch_scc1 .Lcv_sc_m2_p1
	s_cmpk_lt_u32 s95, 0x400
	s_cbranch_scc1 .Lcv_sc_done_p1
	v_add_u32_e32 v168, 0xfffffc00, v168
	v_lshrrev_b32_e32 v169, 5, v168
	v_lshlrev_b32_e32 v169, 4, v169
	v_and_b32_e32 v170, 15, v168
	v_bfe_u32 v171, v168, 4, 1
	v_lshlrev_b32_e32 v171, 10, v171
	v_add3_u32 v168, v169, v170, v171
	v_add_u32_e32 v168, 0x400, v168
	s_branch .Lcv_sc_done_p1

.Lcv_sc_done_p1:
	v_add_u32_e32 v169, s93, v115
	v_mul_lo_u32 v169, v169, s65
	v_add_lshl_u32 v132, v169, v168, 2
	s_lshl_b32 s96, s65, 2
	v_add_u32_e32 v133, s96, v132
	v_add_u32_e32 v134, s96, v133
	v_add_u32_e32 v135, s96, v134
	v_add_u32_e32 v136, s96, v135
	v_add_u32_e32 v137, s96, v136
	v_add_u32_e32 v138, s96, v137
	v_add_u32_e32 v139, s96, v138
	global_load_dword v132, v132, s[60:61]
	global_load_dword v133, v133, s[60:61]
	global_load_dword v134, v134, s[60:61]
	global_load_dword v135, v135, s[60:61]
	global_load_dword v136, v136, s[60:61]
	global_load_dword v137, v137, s[60:61]
	global_load_dword v138, v138, s[60:61]
	global_load_dword v139, v139, s[60:61]
	s_add_i32 s68, s68, s3
	s_cmp_ge_i32 s68, s2
	s_cbranch_scc1 .Lcv_pro_done
	v_cmp_le_i32_e64 s[88:89], v106, s68
	s_nop 1
	s_bcnt1_i32_b64 s74, s[88:89]
	s_sub_u32 s74, s74, 1
	s_nop 3
	v_readlane_b32 s67, v106, s74
	v_readlane_b32 s60, v107, s74
	v_readlane_b32 s61, v108, s74
	v_readlane_b32 s62, v109, s74
	v_readlane_b32 s63, v110, s74
	v_readlane_b32 s64, v111, s74
	v_readlane_b32 s65, v112, s74
	v_readlane_b32 s66, v113, s74
	s_nop 3
	s_sub_u32 s75, s68, s67
	s_lshr_b32 s90, s64, 6
	s_mov_b32 s91, 0x10000000
	s_cmp_eq_u32 s90, 6
	s_cselect_b32 s91, 0x2aaaaaab, s91
	s_cmp_eq_u32 s90, 4
	s_cselect_b32 s91, 0x40000000, s91
	s_cmp_eq_u32 s90, 44
	s_cselect_b32 s91, 0x5d1745e, s91
	s_cmp_eq_u32 s90, 32
	s_cselect_b32 s91, 0x8000000, s91
	s_mul_hi_u32 s92, s75, s91
	s_mul_i32 s93, s92, s90
	s_sub_u32 s93, s75, s93
	s_lshl_b32 s92, s92, 6
	s_lshl_b32 s93, s93, 6
	s_cmp_lt_u32 s92, s65
	s_cselect_b32 s94, -1, 0
	s_cselect_b32 s95, s92, 0
	v_add_u32_e32 v168, s92, v117
	v_mul_lo_u32 v168, v168, s64
	v_add3_u32 v168, v168, v118, s93
	v_lshlrev_b32_e32 v168, 1, v168
	v_mov_b32_e32 v169, 0
	v_lshl_add_u64 v[152:153], v[168:169], 0, s[62:63]
	v_mov_b32_e32 v154, s94
	v_add_u32_e32 v168, s95, v114
	s_cmp_eq_u32 s66, 0
	s_cbranch_scc1 .Lcv_sc_done_p2
	s_cmp_eq_u32 s66, 2
	s_cbranch_scc1 .Lcv_sc_m2_p2
	s_cmpk_lt_u32 s95, 0x400
	s_cbranch_scc1 .Lcv_sc_done_p2
	v_add_u32_e32 v168, 0xfffffc00, v168
	v_lshrrev_b32_e32 v169, 5, v168
	v_lshlrev_b32_e32 v169, 4, v169
	v_and_b32_e32 v170, 15, v168
	v_bfe_u32 v171, v168, 4, 1
	v_lshlrev_b32_e32 v171, 10, v171
	v_add3_u32 v168, v169, v170, v171
	v_add_u32_e32 v168, 0x400, v168
	s_branch .Lcv_sc_done_p2

.Lcv_sc_done_p2:
	v_add_u32_e32 v169, s93, v115
	v_mul_lo_u32 v169, v169, s65
	v_add_lshl_u32 v144, v169, v168, 2
	s_lshl_b32 s96, s65, 2
	v_add_u32_e32 v145, s96, v144
	v_add_u32_e32 v146, s96, v145
	v_add_u32_e32 v147, s96, v146
	v_add_u32_e32 v148, s96, v147
	v_add_u32_e32 v149, s96, v148
	v_add_u32_e32 v150, s96, v149
	v_add_u32_e32 v151, s96, v150
	global_load_dword v144, v144, s[60:61]
	global_load_dword v145, v145, s[60:61]
	global_load_dword v146, v146, s[60:61]
	global_load_dword v147, v147, s[60:61]
	global_load_dword v148, v148, s[60:61]
	global_load_dword v149, v149, s[60:61]
	global_load_dword v150, v150, s[60:61]
	global_load_dword v151, v151, s[60:61]
	s_add_i32 s68, s68, s3
	s_cmp_ge_i32 s68, s2
	s_cbranch_scc1 .Lcv_pro_done
	v_cmp_le_i32_e64 s[88:89], v106, s68
	s_nop 1
	s_bcnt1_i32_b64 s74, s[88:89]
	s_sub_u32 s74, s74, 1
	s_nop 3
	v_readlane_b32 s67, v106, s74
	v_readlane_b32 s60, v107, s74
	v_readlane_b32 s61, v108, s74
	v_readlane_b32 s62, v109, s74
	v_readlane_b32 s63, v110, s74
	v_readlane_b32 s64, v111, s74
	v_readlane_b32 s65, v112, s74
	v_readlane_b32 s66, v113, s74
	s_nop 3
	s_sub_u32 s75, s68, s67
	s_lshr_b32 s90, s64, 6
	s_mov_b32 s91, 0x10000000
	s_cmp_eq_u32 s90, 6
	s_cselect_b32 s91, 0x2aaaaaab, s91
	s_cmp_eq_u32 s90, 4
	s_cselect_b32 s91, 0x40000000, s91
	s_cmp_eq_u32 s90, 44
	s_cselect_b32 s91, 0x5d1745e, s91
	s_cmp_eq_u32 s90, 32
	s_cselect_b32 s91, 0x8000000, s91
	s_mul_hi_u32 s92, s75, s91
	s_mul_i32 s93, s92, s90
	s_sub_u32 s93, s75, s93
	s_lshl_b32 s92, s92, 6
	s_lshl_b32 s93, s93, 6
	s_cmp_lt_u32 s92, s65
	s_cselect_b32 s94, -1, 0
	s_cselect_b32 s95, s92, 0
	v_add_u32_e32 v168, s92, v117
	v_mul_lo_u32 v168, v168, s64
	v_add3_u32 v168, v168, v118, s93
	v_lshlrev_b32_e32 v168, 1, v168
	v_mov_b32_e32 v169, 0
	v_lshl_add_u64 v[164:165], v[168:169], 0, s[62:63]
	v_mov_b32_e32 v166, s94
	v_add_u32_e32 v168, s95, v114
	s_cmp_eq_u32 s66, 0
	s_cbranch_scc1 .Lcv_sc_done_p3
	s_cmp_eq_u32 s66, 2
	s_cbranch_scc1 .Lcv_sc_m2_p3
	s_cmpk_lt_u32 s95, 0x400
	s_cbranch_scc1 .Lcv_sc_done_p3
	v_add_u32_e32 v168, 0xfffffc00, v168
	v_lshrrev_b32_e32 v169, 5, v168
	v_lshlrev_b32_e32 v169, 4, v169
	v_and_b32_e32 v170, 15, v168
	v_bfe_u32 v171, v168, 4, 1
	v_lshlrev_b32_e32 v171, 10, v171
	v_add3_u32 v168, v169, v170, v171
	v_add_u32_e32 v168, 0x400, v168
	s_branch .Lcv_sc_done_p3

.Lcv_sc_done_p3:
	v_add_u32_e32 v169, s93, v115
	v_mul_lo_u32 v169, v169, s65
	v_add_lshl_u32 v156, v169, v168, 2
	s_lshl_b32 s96, s65, 2
	v_add_u32_e32 v157, s96, v156
	v_add_u32_e32 v158, s96, v157
	v_add_u32_e32 v159, s96, v158
	v_add_u32_e32 v160, s96, v159
	v_add_u32_e32 v161, s96, v160
	v_add_u32_e32 v162, s96, v161
	v_add_u32_e32 v163, s96, v162
	global_load_dword v156, v156, s[60:61]
	global_load_dword v157, v157, s[60:61]
	global_load_dword v158, v158, s[60:61]
	global_load_dword v159, v159, s[60:61]
	global_load_dword v160, v160, s[60:61]
	global_load_dword v161, v161, s[60:61]
	global_load_dword v162, v162, s[60:61]
	global_load_dword v163, v163, s[60:61]
	s_add_i32 s68, s68, s3
.Lcv_pro_done:
.Lcv_loop:
	s_cmp_ge_i32 s69, s2
	s_cbranch_scc1 .Lcv_done
	s_add_i32 s74, s69, s72
	s_cmp_lt_i32 s74, s2
	s_cbranch_scc1 .Lcv_w24_0
	s_waitcnt vmcnt(0)
	s_branch .Lcv_go_0
.Lcv_w24_0:
	s_waitcnt vmcnt(24)
.Lcv_go_0:
	v_and_b32_e32 v120, v130, v120
	v_and_b32_e32 v121, v130, v121
	v_and_b32_e32 v122, v130, v122
	v_and_b32_e32 v123, v130, v123
	v_and_b32_e32 v124, v130, v124
	v_and_b32_e32 v125, v130, v125
	v_and_b32_e32 v126, v130, v126
	v_and_b32_e32 v127, v130, v127
	ds_write_b32 v116, v120 offset:0
	ds_write_b32 v116, v121 offset:260
	ds_write_b32 v116, v122 offset:520
	ds_write_b32 v116, v123 offset:780
	ds_write_b32 v116, v124 offset:1040
	ds_write_b32 v116, v125 offset:1300
	ds_write_b32 v116, v126 offset:1560
	ds_write_b32 v116, v127 offset:1820
	s_waitcnt lgkmcnt(0)
	s_barrier
	ds_read2_b32 v[176:177], v119 offset1:65
	ds_read2_b32 v[178:179], v119 offset0:130 offset1:195
	ds_read2_b32 v[180:181], v131 offset1:65
	ds_read2_b32 v[182:183], v131 offset0:130 offset1:195
	s_waitcnt lgkmcnt(3)
	v_cvt_pk_bf16_f32 v172, v176, v177
	s_waitcnt lgkmcnt(2)
	v_cvt_pk_bf16_f32 v173, v178, v179
	s_waitcnt lgkmcnt(1)
	v_cvt_pk_bf16_f32 v174, v180, v181
	s_waitcnt lgkmcnt(0)
	v_cvt_pk_bf16_f32 v175, v182, v183
	global_store_dwordx4 v[128:129], v[172:175], off
	s_add_i32 s69, s69, s3
	s_cmp_ge_i32 s68, s2
	s_cbranch_scc1 .Lcv_nodec_0
	v_cmp_le_i32_e64 s[88:89], v106, s68
	s_nop 1
	s_bcnt1_i32_b64 s74, s[88:89]
	s_sub_u32 s74, s74, 1
	s_nop 3
	v_readlane_b32 s67, v106, s74
	v_readlane_b32 s60, v107, s74
	v_readlane_b32 s61, v108, s74
	v_readlane_b32 s62, v109, s74
	v_readlane_b32 s63, v110, s74
	v_readlane_b32 s64, v111, s74
	v_readlane_b32 s65, v112, s74
	v_readlane_b32 s66, v113, s74
	s_nop 3
	s_sub_u32 s75, s68, s67
	s_lshr_b32 s90, s64, 6
	s_mov_b32 s91, 0x10000000
	s_cmp_eq_u32 s90, 6
	s_cselect_b32 s91, 0x2aaaaaab, s91
	s_cmp_eq_u32 s90, 4
	s_cselect_b32 s91, 0x40000000, s91
	s_cmp_eq_u32 s90, 44
	s_cselect_b32 s91, 0x5d1745e, s91
	s_cmp_eq_u32 s90, 32
	s_cselect_b32 s91, 0x8000000, s91
	s_mul_hi_u32 s92, s75, s91
	s_mul_i32 s93, s92, s90
	s_sub_u32 s93, s75, s93
	s_lshl_b32 s92, s92, 6
	s_lshl_b32 s93, s93, 6
	s_cmp_lt_u32 s92, s65
	s_cselect_b32 s94, -1, 0
	s_cselect_b32 s95, s92, 0
	v_add_u32_e32 v168, s92, v117
	v_mul_lo_u32 v168, v168, s64
	v_add3_u32 v168, v168, v118, s93
	v_lshlrev_b32_e32 v168, 1, v168
	v_mov_b32_e32 v169, 0
	v_lshl_add_u64 v[128:129], v[168:169], 0, s[62:63]
	v_mov_b32_e32 v130, s94
	v_add_u32_e32 v168, s95, v114
	s_cmp_eq_u32 s66, 0
	s_cbranch_scc1 .Lcv_sc_done_l0
	s_cmp_eq_u32 s66, 2
	s_cbranch_scc1 .Lcv_sc_m2_l0
	s_cmpk_lt_u32 s95, 0x400
	s_cbranch_scc1 .Lcv_sc_done_l0
	v_add_u32_e32 v168, 0xfffffc00, v168
	v_lshrrev_b32_e32 v169, 5, v168
	v_lshlrev_b32_e32 v169, 4, v169
	v_and_b32_e32 v170, 15, v168
	v_bfe_u32 v171, v168, 4, 1
	v_lshlrev_b32_e32 v171, 10, v171
	v_add3_u32 v168, v169, v170, v171
	v_add_u32_e32 v168, 0x400, v168
	s_branch .Lcv_sc_done_l0

.Lcv_sc_done_l0:
	v_add_u32_e32 v169, s93, v115
	v_mul_lo_u32 v169, v169, s65
	v_add_lshl_u32 v120, v169, v168, 2
	s_lshl_b32 s96, s65, 2
	v_add_u32_e32 v121, s96, v120
	v_add_u32_e32 v122, s96, v121
	v_add_u32_e32 v123, s96, v122
	v_add_u32_e32 v124, s96, v123
	v_add_u32_e32 v125, s96, v124
	v_add_u32_e32 v126, s96, v125
	v_add_u32_e32 v127, s96, v126
	global_load_dword v120, v120, s[60:61]
	global_load_dword v121, v121, s[60:61]
	global_load_dword v122, v122, s[60:61]
	global_load_dword v123, v123, s[60:61]
	global_load_dword v124, v124, s[60:61]
	global_load_dword v125, v125, s[60:61]
	global_load_dword v126, v126, s[60:61]
	global_load_dword v127, v127, s[60:61]
	s_add_i32 s68, s68, s3
.Lcv_nodec_0:
	s_cmp_ge_i32 s69, s2
	s_cbranch_scc1 .Lcv_done
	s_add_i32 s74, s69, s72
	s_cmp_lt_i32 s74, s2
	s_cbranch_scc1 .Lcv_w24_1
	s_waitcnt vmcnt(0)
	s_branch .Lcv_go_1

.Lcv_go_1:
	v_and_b32_e32 v132, v142, v132
	v_and_b32_e32 v133, v142, v133
	v_and_b32_e32 v134, v142, v134
	v_and_b32_e32 v135, v142, v135
	v_and_b32_e32 v136, v142, v136
	v_and_b32_e32 v137, v142, v137
	v_and_b32_e32 v138, v142, v138
	v_and_b32_e32 v139, v142, v139
	ds_write_b32 v116, v132 offset:16640
	ds_write_b32 v116, v133 offset:16900
	ds_write_b32 v116, v134 offset:17160
	ds_write_b32 v116, v135 offset:17420
	ds_write_b32 v116, v136 offset:17680
	ds_write_b32 v116, v137 offset:17940
	ds_write_b32 v116, v138 offset:18200
	ds_write_b32 v116, v139 offset:18460
	s_waitcnt lgkmcnt(0)
	s_barrier
	ds_read2_b32 v[176:177], v143 offset1:65
	ds_read2_b32 v[178:179], v143 offset0:130 offset1:195
	ds_read2_b32 v[180:181], v155 offset1:65
	ds_read2_b32 v[182:183], v155 offset0:130 offset1:195
	s_waitcnt lgkmcnt(3)
	v_cvt_pk_bf16_f32 v172, v176, v177
	s_waitcnt lgkmcnt(2)
	v_cvt_pk_bf16_f32 v173, v178, v179
	s_waitcnt lgkmcnt(1)
	v_cvt_pk_bf16_f32 v174, v180, v181
	s_waitcnt lgkmcnt(0)
	v_cvt_pk_bf16_f32 v175, v182, v183
	global_store_dwordx4 v[140:141], v[172:175], off
	s_add_i32 s69, s69, s3
	s_cmp_ge_i32 s68, s2
	s_cbranch_scc1 .Lcv_nodec_1
	v_cmp_le_i32_e64 s[88:89], v106, s68
	s_nop 1
	s_bcnt1_i32_b64 s74, s[88:89]
	s_sub_u32 s74, s74, 1
	s_nop 3
	v_readlane_b32 s67, v106, s74
	v_readlane_b32 s60, v107, s74
	v_readlane_b32 s61, v108, s74
	v_readlane_b32 s62, v109, s74
	v_readlane_b32 s63, v110, s74
	v_readlane_b32 s64, v111, s74
	v_readlane_b32 s65, v112, s74
	v_readlane_b32 s66, v113, s74
	s_nop 3
	s_sub_u32 s75, s68, s67
	s_lshr_b32 s90, s64, 6
	s_mov_b32 s91, 0x10000000
	s_cmp_eq_u32 s90, 6
	s_cselect_b32 s91, 0x2aaaaaab, s91
	s_cmp_eq_u32 s90, 4
	s_cselect_b32 s91, 0x40000000, s91
	s_cmp_eq_u32 s90, 44
	s_cselect_b32 s91, 0x5d1745e, s91
	s_cmp_eq_u32 s90, 32
	s_cselect_b32 s91, 0x8000000, s91
	s_mul_hi_u32 s92, s75, s91
	s_mul_i32 s93, s92, s90
	s_sub_u32 s93, s75, s93
	s_lshl_b32 s92, s92, 6
	s_lshl_b32 s93, s93, 6
	s_cmp_lt_u32 s92, s65
	s_cselect_b32 s94, -1, 0
	s_cselect_b32 s95, s92, 0
	v_add_u32_e32 v168, s92, v117
	v_mul_lo_u32 v168, v168, s64
	v_add3_u32 v168, v168, v118, s93
	v_lshlrev_b32_e32 v168, 1, v168
	v_mov_b32_e32 v169, 0
	v_lshl_add_u64 v[140:141], v[168:169], 0, s[62:63]
	v_mov_b32_e32 v142, s94
	v_add_u32_e32 v168, s95, v114
	s_cmp_eq_u32 s66, 0
	s_cbranch_scc1 .Lcv_sc_done_l1
	s_cmp_eq_u32 s66, 2
	s_cbranch_scc1 .Lcv_sc_m2_l1
	s_cmpk_lt_u32 s95, 0x400
	s_cbranch_scc1 .Lcv_sc_done_l1
	v_add_u32_e32 v168, 0xfffffc00, v168
	v_lshrrev_b32_e32 v169, 5, v168
	v_lshlrev_b32_e32 v169, 4, v169
	v_and_b32_e32 v170, 15, v168
	v_bfe_u32 v171, v168, 4, 1
	v_lshlrev_b32_e32 v171, 10, v171
	v_add3_u32 v168, v169, v170, v171
	v_add_u32_e32 v168, 0x400, v168
	s_branch .Lcv_sc_done_l1

.Lcv_sc_done_l1:
	v_add_u32_e32 v169, s93, v115
	v_mul_lo_u32 v169, v169, s65
	v_add_lshl_u32 v132, v169, v168, 2
	s_lshl_b32 s96, s65, 2
	v_add_u32_e32 v133, s96, v132
	v_add_u32_e32 v134, s96, v133
	v_add_u32_e32 v135, s96, v134
	v_add_u32_e32 v136, s96, v135
	v_add_u32_e32 v137, s96, v136
	v_add_u32_e32 v138, s96, v137
	v_add_u32_e32 v139, s96, v138
	global_load_dword v132, v132, s[60:61]
	global_load_dword v133, v133, s[60:61]
	global_load_dword v134, v134, s[60:61]
	global_load_dword v135, v135, s[60:61]
	global_load_dword v136, v136, s[60:61]
	global_load_dword v137, v137, s[60:61]
	global_load_dword v138, v138, s[60:61]
	global_load_dword v139, v139, s[60:61]
	s_add_i32 s68, s68, s3

.Lcv_go_2:
	v_and_b32_e32 v144, v154, v144
	v_and_b32_e32 v145, v154, v145
	v_and_b32_e32 v146, v154, v146
	v_and_b32_e32 v147, v154, v147
	v_and_b32_e32 v148, v154, v148
	v_and_b32_e32 v149, v154, v149
	v_and_b32_e32 v150, v154, v150
	v_and_b32_e32 v151, v154, v151
	ds_write_b32 v116, v144 offset:0
	ds_write_b32 v116, v145 offset:260
	ds_write_b32 v116, v146 offset:520
	ds_write_b32 v116, v147 offset:780
	ds_write_b32 v116, v148 offset:1040
	ds_write_b32 v116, v149 offset:1300
	ds_write_b32 v116, v150 offset:1560
	ds_write_b32 v116, v151 offset:1820
	s_waitcnt lgkmcnt(0)
	s_barrier
	ds_read2_b32 v[176:177], v119 offset1:65
	ds_read2_b32 v[178:179], v119 offset0:130 offset1:195
	ds_read2_b32 v[180:181], v131 offset1:65
	ds_read2_b32 v[182:183], v131 offset0:130 offset1:195
	s_waitcnt lgkmcnt(3)
	v_cvt_pk_bf16_f32 v172, v176, v177
	s_waitcnt lgkmcnt(2)
	v_cvt_pk_bf16_f32 v173, v178, v179
	s_waitcnt lgkmcnt(1)
	v_cvt_pk_bf16_f32 v174, v180, v181
	s_waitcnt lgkmcnt(0)
	v_cvt_pk_bf16_f32 v175, v182, v183
	global_store_dwordx4 v[152:153], v[172:175], off
	s_add_i32 s69, s69, s3
	s_cmp_ge_i32 s68, s2
	s_cbranch_scc1 .Lcv_nodec_2
	v_cmp_le_i32_e64 s[88:89], v106, s68
	s_nop 1
	s_bcnt1_i32_b64 s74, s[88:89]
	s_sub_u32 s74, s74, 1
	s_nop 3
	v_readlane_b32 s67, v106, s74
	v_readlane_b32 s60, v107, s74
	v_readlane_b32 s61, v108, s74
	v_readlane_b32 s62, v109, s74
	v_readlane_b32 s63, v110, s74
	v_readlane_b32 s64, v111, s74
	v_readlane_b32 s65, v112, s74
	v_readlane_b32 s66, v113, s74
	s_nop 3
	s_sub_u32 s75, s68, s67
	s_lshr_b32 s90, s64, 6
	s_mov_b32 s91, 0x10000000
	s_cmp_eq_u32 s90, 6
	s_cselect_b32 s91, 0x2aaaaaab, s91
	s_cmp_eq_u32 s90, 4
	s_cselect_b32 s91, 0x40000000, s91
	s_cmp_eq_u32 s90, 44
	s_cselect_b32 s91, 0x5d1745e, s91
	s_cmp_eq_u32 s90, 32
	s_cselect_b32 s91, 0x8000000, s91
	s_mul_hi_u32 s92, s75, s91
	s_mul_i32 s93, s92, s90
	s_sub_u32 s93, s75, s93
	s_lshl_b32 s92, s92, 6
	s_lshl_b32 s93, s93, 6
	s_cmp_lt_u32 s92, s65
	s_cselect_b32 s94, -1, 0
	s_cselect_b32 s95, s92, 0
	v_add_u32_e32 v168, s92, v117
	v_mul_lo_u32 v168, v168, s64
	v_add3_u32 v168, v168, v118, s93
	v_lshlrev_b32_e32 v168, 1, v168
	v_mov_b32_e32 v169, 0
	v_lshl_add_u64 v[152:153], v[168:169], 0, s[62:63]
	v_mov_b32_e32 v154, s94
	v_add_u32_e32 v168, s95, v114
	s_cmp_eq_u32 s66, 0
	s_cbranch_scc1 .Lcv_sc_done_l2
	s_cmp_eq_u32 s66, 2
	s_cbranch_scc1 .Lcv_sc_m2_l2
	s_cmpk_lt_u32 s95, 0x400
	s_cbranch_scc1 .Lcv_sc_done_l2
	v_add_u32_e32 v168, 0xfffffc00, v168
	v_lshrrev_b32_e32 v169, 5, v168
	v_lshlrev_b32_e32 v169, 4, v169
	v_and_b32_e32 v170, 15, v168
	v_bfe_u32 v171, v168, 4, 1
	v_lshlrev_b32_e32 v171, 10, v171
	v_add3_u32 v168, v169, v170, v171
	v_add_u32_e32 v168, 0x400, v168
	s_branch .Lcv_sc_done_l2

.Lcv_sc_done_l2:
	v_add_u32_e32 v169, s93, v115
	v_mul_lo_u32 v169, v169, s65
	v_add_lshl_u32 v144, v169, v168, 2
	s_lshl_b32 s96, s65, 2
	v_add_u32_e32 v145, s96, v144
	v_add_u32_e32 v146, s96, v145
	v_add_u32_e32 v147, s96, v146
	v_add_u32_e32 v148, s96, v147
	v_add_u32_e32 v149, s96, v148
	v_add_u32_e32 v150, s96, v149
	v_add_u32_e32 v151, s96, v150
	global_load_dword v144, v144, s[60:61]
	global_load_dword v145, v145, s[60:61]
	global_load_dword v146, v146, s[60:61]
	global_load_dword v147, v147, s[60:61]
	global_load_dword v148, v148, s[60:61]
	global_load_dword v149, v149, s[60:61]
	global_load_dword v150, v150, s[60:61]
	global_load_dword v151, v151, s[60:61]
	s_add_i32 s68, s68, s3

.Lcv_go_3:
	v_and_b32_e32 v156, v166, v156
	v_and_b32_e32 v157, v166, v157
	v_and_b32_e32 v158, v166, v158
	v_and_b32_e32 v159, v166, v159
	v_and_b32_e32 v160, v166, v160
	v_and_b32_e32 v161, v166, v161
	v_and_b32_e32 v162, v166, v162
	v_and_b32_e32 v163, v166, v163
	ds_write_b32 v116, v156 offset:16640
	ds_write_b32 v116, v157 offset:16900
	ds_write_b32 v116, v158 offset:17160
	ds_write_b32 v116, v159 offset:17420
	ds_write_b32 v116, v160 offset:17680
	ds_write_b32 v116, v161 offset:17940
	ds_write_b32 v116, v162 offset:18200
	ds_write_b32 v116, v163 offset:18460
	s_waitcnt lgkmcnt(0)
	s_barrier
	ds_read2_b32 v[176:177], v143 offset1:65
	ds_read2_b32 v[178:179], v143 offset0:130 offset1:195
	ds_read2_b32 v[180:181], v155 offset1:65
	ds_read2_b32 v[182:183], v155 offset0:130 offset1:195
	s_waitcnt lgkmcnt(3)
	v_cvt_pk_bf16_f32 v172, v176, v177
	s_waitcnt lgkmcnt(2)
	v_cvt_pk_bf16_f32 v173, v178, v179
	s_waitcnt lgkmcnt(1)
	v_cvt_pk_bf16_f32 v174, v180, v181
	s_waitcnt lgkmcnt(0)
	v_cvt_pk_bf16_f32 v175, v182, v183
	global_store_dwordx4 v[164:165], v[172:175], off
	s_add_i32 s69, s69, s3
	s_cmp_ge_i32 s68, s2
	s_cbranch_scc1 .Lcv_nodec_3
	v_cmp_le_i32_e64 s[88:89], v106, s68
	s_nop 1
	s_bcnt1_i32_b64 s74, s[88:89]
	s_sub_u32 s74, s74, 1
	s_nop 3
	v_readlane_b32 s67, v106, s74
	v_readlane_b32 s60, v107, s74
	v_readlane_b32 s61, v108, s74
	v_readlane_b32 s62, v109, s74
	v_readlane_b32 s63, v110, s74
	v_readlane_b32 s64, v111, s74
	v_readlane_b32 s65, v112, s74
	v_readlane_b32 s66, v113, s74
	s_nop 3
	s_sub_u32 s75, s68, s67
	s_lshr_b32 s90, s64, 6
	s_mov_b32 s91, 0x10000000
	s_cmp_eq_u32 s90, 6
	s_cselect_b32 s91, 0x2aaaaaab, s91
	s_cmp_eq_u32 s90, 4
	s_cselect_b32 s91, 0x40000000, s91
	s_cmp_eq_u32 s90, 44
	s_cselect_b32 s91, 0x5d1745e, s91
	s_cmp_eq_u32 s90, 32
	s_cselect_b32 s91, 0x8000000, s91
	s_mul_hi_u32 s92, s75, s91
	s_mul_i32 s93, s92, s90
	s_sub_u32 s93, s75, s93
	s_lshl_b32 s92, s92, 6
	s_lshl_b32 s93, s93, 6
	s_cmp_lt_u32 s92, s65
	s_cselect_b32 s94, -1, 0
	s_cselect_b32 s95, s92, 0
	v_add_u32_e32 v168, s92, v117
	v_mul_lo_u32 v168, v168, s64
	v_add3_u32 v168, v168, v118, s93
	v_lshlrev_b32_e32 v168, 1, v168
	v_mov_b32_e32 v169, 0
	v_lshl_add_u64 v[164:165], v[168:169], 0, s[62:63]
	v_mov_b32_e32 v166, s94
	v_add_u32_e32 v168, s95, v114
	s_cmp_eq_u32 s66, 0
	s_cbranch_scc1 .Lcv_sc_done_l3
	s_cmp_eq_u32 s66, 2
	s_cbranch_scc1 .Lcv_sc_m2_l3
	s_cmpk_lt_u32 s95, 0x400
	s_cbranch_scc1 .Lcv_sc_done_l3
	v_add_u32_e32 v168, 0xfffffc00, v168
	v_lshrrev_b32_e32 v169, 5, v168
	v_lshlrev_b32_e32 v169, 4, v169
	v_and_b32_e32 v170, 15, v168
	v_bfe_u32 v171, v168, 4, 1
	v_lshlrev_b32_e32 v171, 10, v171
	v_add3_u32 v168, v169, v170, v171
	v_add_u32_e32 v168, 0x400, v168
	s_branch .Lcv_sc_done_l3

.Lcv_done:
	s_waitcnt vmcnt(0)
	s_barrier
	s_sub_i32 s50, s69, s3
	s_branch .LBB0_10
